# v80 + nt on the output LayerNorm's residual-row loads (last read of those rows)
# speedup vs baseline: 1.0025x; 1.0022x over previous
; #define GAS __attribute__((address_space(1)))
; #define KIN(i) ((const float*)karg(i))
; __device__ __forceinline__ void ln_rows_b(const Frame& F, const bf16* src, float* dstf, bf16* dstb, float* must, const float* gam, const float* bet, int nrows, bool poison) {
;     const int gw = F.vcu * NWAVES + F.wave, NGW = F.G * NWAVES;
;     v4u wn[4];
;     if (gw < nrows) { const GAS v4u* xr = (const GAS v4u*)(src + (size_t)gw * DM) + F.lane;
; #pragma unroll
;         for (int j = 0; j < 4; ++j) wn[j] = xr[64 * j]; }
; __global__ void __launch_bounds__(NWAVES * 64, 2) fwd_kernel(Args args) {
;     ...
;                 if (c > 0) ln_rows_b(F, P_RB, KOUT + (size_t)(c - 1) * TC * DM, nullptr, nullptr, KIN(16) + DM, KIN(17) + DM, TC, false);
.LBB0_210:
	s_cmp_lt_u32 s61, 2
	s_cbranch_scc1 .LBB0_218
	s_mov_b32 s18, 33
	s_mov_b32 s16, 18
	s_mov_b32 s14, 16
	s_mov_b32 s6, 17
	s_andn2_b64 vcc, exec, s[12:13]
	s_cbranch_vccnz .LBB0_218
	s_ashr_i32 s19, s18, 31
	s_lshl_b64 s[12:13], s[18:19], 3
	s_add_u32 s12, s0, s12
	s_addc_u32 s13, s1, s13
	s_ashr_i32 s17, s16, 31
	s_lshl_b64 s[16:17], s[16:17], 3
	s_add_u32 s16, s0, s16
	s_addc_u32 s17, s1, s17
	s_ashr_i32 s15, s14, 31
	s_lshl_b64 s[14:15], s[14:15], 3
	s_add_u32 s14, s0, s14
	s_addc_u32 s15, s1, s15
	s_add_i32 s84, s39, -1
	s_ashr_i32 s7, s6, 31
	s_lshl_b64 s[18:19], s[84:85], 27
	s_lshl_b64 s[6:7], s[6:7], 3
	s_add_u32 s6, s0, s6
	s_addc_u32 s7, s1, s7
	s_load_dwordx2 s[6:7], s[6:7], 0x0
	s_nop 0
	s_load_dwordx2 s[14:15], s[14:15], 0x0
	s_nop 0
	s_load_dwordx2 s[20:21], s[12:13], 0x0
	s_nop 0
	s_load_dwordx2 s[16:17], s[16:17], 0x0
	v_lshlrev_b32_e32 v2, 4, v226
	s_waitcnt lgkmcnt(0)
	s_add_u32 s6, s6, 0x2000
	s_addc_u32 s7, s7, 0
	s_add_u32 s14, s14, 0x2000
	s_addc_u32 s15, s15, 0
	s_ashr_i32 s9, s8, 31
	s_lshl_b64 s[12:13], s[8:9], 12
	s_add_u32 s12, s20, s12
	s_addc_u32 s13, s21, s13
	global_load_dwordx4 v[30:33], v2, s[12:13] nt
	global_load_dwordx4 v[26:29], v2, s[12:13] offset:1024 nt
	global_load_dwordx4 v[22:25], v2, s[12:13] offset:2048 nt
	global_load_dwordx4 v[18:21], v2, s[12:13] offset:3072 nt
	v_lshlrev_b32_e32 v4, 2, v226
	v_lshlrev_b32_e32 v226, 5, v226
	v_xor_b32_e32 v1, 4, v4
	v_xor_b32_e32 v70, 8, v4
	v_xor_b32_e32 v71, 16, v4
	v_xor_b32_e32 v72, 32, v4
	v_xor_b32_e32 v73, 64, v4
	v_xor_b32_e32 v74, 0x80, v4
	v_or_b32_e32 v4, 0x800, v226
	v_mov_b32_e32 v5, v227
	v_lshl_add_u64 v[38:39], s[6:7], 0, v[4:5]
	v_lshl_add_u64 v[40:41], s[14:15], 0, v[4:5]
	v_or_b32_e32 v4, 0x1000, v226
	s_cmp_lg_u64 s[16:17], 0
	v_lshl_add_u64 v[42:43], s[6:7], 0, v[4:5]
	v_lshl_add_u64 v[44:45], s[14:15], 0, v[4:5]
	v_or_b32_e32 v4, 0x1800, v226
	s_cselect_b64 s[12:13], -1, 0
	v_lshl_add_u64 v[34:35], s[6:7], 0, v[226:227]
	v_lshl_add_u64 v[46:47], s[6:7], 0, v[4:5]
	s_lshl_b64 s[6:7], s[8:9], 13
	s_add_u32 s6, s18, s6
	s_addc_u32 s7, s19, s7
	s_add_u32 s6, s16, s6
	s_addc_u32 s7, s17, s7
	v_lshl_add_u64 v[48:49], s[14:15], 0, v[4:5]
	v_lshl_add_u64 v[4:5], s[6:7], 0, v[226:227]
	s_mov_b64 s[6:7], 0x1000
	v_lshl_add_u64 v[50:51], v[4:5], 0, s[6:7]
	s_add_i32 s6, s8, s10
	s_ashr_i32 s11, s10, 31
	s_ashr_i32 s7, s6, 31
	v_lshl_add_u64 v[36:37], s[14:15], 0, v[226:227]
	s_lshl_b64 s[14:15], s[10:11], 13
	s_lshl_b64 s[6:7], s[6:7], 12
	s_add_u32 s6, s20, s6
	v_mov_b32_e32 v3, v227
	s_addc_u32 s7, s21, s7
	v_lshl_add_u64 v[2:3], s[6:7], 0, v[2:3]
	s_mov_b64 s[6:7], 0x800
	v_lshl_add_u64 v[52:53], v[2:3], 0, s[6:7]
	s_lshl_b64 s[16:17], s[10:11], 12
	s_branch .LBB0_214

; #define GAS __attribute__((address_space(1)))
; __device__ __forceinline__ void ln_rows_b(const Frame& F, const bf16* src, float* dstf, bf16* dstb, float* must, const float* gam, const float* bet, int nrows, bool poison) {
;     ...
;     for (int m = gw; m < nrows; m += NGW) {
;         v4u wc[4];
; #pragma unroll
;         for (int j = 0; j < 4; ++j) wc[j] = wn[j];
;         if (m + NGW < nrows) { const GAS v4u* xr = (const GAS v4u*)(src + (size_t)(m + NGW) * DM) + F.lane;
; #pragma unroll
;             for (int j = 0; j < 4; ++j) wn[j] = xr[64 * j]; }
.LBB0_214:
	s_add_i32 s8, s8, s10
	s_cmpk_gt_i32 s8, 0x3fff
	s_cselect_b64 s[18:19], -1, 0
	s_and_b64 vcc, exec, s[18:19]
	s_waitcnt vmcnt(0)
	v_mov_b32_e32 v2, v30
	v_mov_b32_e32 v3, v31
	v_mov_b32_e32 v4, v32
	v_mov_b32_e32 v5, v33
	v_mov_b32_e32 v6, v26
	v_mov_b32_e32 v7, v27
	v_mov_b32_e32 v8, v28
	v_mov_b32_e32 v9, v29
	v_mov_b32_e32 v10, v22
	v_mov_b32_e32 v11, v23
	v_mov_b32_e32 v12, v24
	v_mov_b32_e32 v13, v25
	v_mov_b32_e32 v14, v18
	v_mov_b32_e32 v15, v19
	v_mov_b32_e32 v16, v20
	v_mov_b32_e32 v17, v21
	s_cbranch_vccnz .LBB0_216
	global_load_dwordx4 v[2:5], v[52:53], off offset:-2048 nt
	global_load_dwordx4 v[6:9], v[52:53], off offset:-1024 nt
	global_load_dwordx4 v[10:13], v[52:53], off nt
	global_load_dwordx4 v[14:17], v[52:53], off offset:1024 nt
